# rowpass: global loads + counted vmcnt so next-row prefetch stays in flight through the row; attention: Q/rope/sink loads hoisted into one wait, K/V prefetch as global loads
# speedup vs baseline: 1.0005x; 1.0005x over previous
; DI unsigned pk_bf16(float lo, float hi) { unsigned r; asm("v_cvt_pk_bf16_f32 %0, %1, %2" : "=v"(r) : "v"(lo), "v"(hi)); return r; }
; DI void phase_rowpass(unsigned char* ws, int nrows, const float* xin_lat, const float* xin_ctx, const float* y, const float* gate_base  ,
;                       const float* gpost, bool write_x, bool write_h, const float* hmod_base  , int sc_which, int sh_which, const float* gpre) {
;     ...
;         if (write_h) {
;             float ss = 0.f;
; #pragma unroll
;             for (int i = 0; i < 4; ++i) ss += xv[i][0] * xv[i][0] + xv[i][1] * xv[i][1] + xv[i][2] * xv[i][2] + xv[i][3] * xv[i][3];
;             ss = wave_sum(ss);
;             const float rs = rsqrtf(ss * (1.f / 1024.f) + eps);
; #pragma unroll
;             for (int i = 0; i < 4; ++i) {
;                 float hv[4];
; #pragma unroll
;                 for (int j = 0; j < 4; ++j) hv[j] = (xv[i][j] * rs * vpre[i][j]) * (1.f + vsc[i][j]) + vsh[i][j];
;                 u32x2 o; o[0] = pk_bf16(hv[0], hv[1]); o[1] = pk_bf16(hv[2], hv[3]);
;                 *(u32x2*)(H + (size_t)r * 1024 + i * 256 + lane * 4) = o;
;             }
;         }
; #pragma unroll
;         for (int i = 0; i < 4; ++i) { xv[i] = xnx[i]; yv[i] = ynx[i]; }
.LBB0_64:
	s_or_b64 exec, exec, s[42:43]
	s_nop 0
	v_pk_mul_f32 v[104:105], v[78:79], v[78:79]
	v_pk_mul_f32 v[106:107], v[74:75], v[74:75]
	v_pk_mul_f32 v[100:101], v[80:81], v[80:81]
	v_pk_mul_f32 v[102:103], v[76:77], v[76:77]
	v_mov_b32_e32 v108, v104
	v_mov_b32_e32 v109, v106
	v_mov_b32_e32 v106, v105
	v_pk_add_f32 v[104:105], v[108:109], v[106:107]
	v_mov_b32_e32 v106, v100
	v_mov_b32_e32 v107, v102
	v_pk_mul_f32 v[96:97], v[18:19], v[18:19]
	v_pk_mul_f32 v[98:99], v[62:63], v[62:63]
	v_pk_add_f32 v[104:105], v[106:107], v[104:105]
	v_mov_b32_e32 v102, v101
	v_pk_mul_f32 v[88:89], v[20:21], v[20:21]
	v_pk_mul_f32 v[94:95], v[64:65], v[64:65]
	v_pk_add_f32 v[100:101], v[102:103], v[104:105]
	v_mov_b32_e32 v102, v96
	v_mov_b32_e32 v103, v98
	v_mov_b32_e32 v98, v97
	v_pk_add_f32 v[96:97], v[102:103], v[98:99]
	v_mov_b32_e32 v98, v88
	v_mov_b32_e32 v99, v94
	v_pk_add_f32 v[96:97], v[98:99], v[96:97]
	v_mov_b32_e32 v94, v89
	v_pk_add_f32 v[88:89], v[94:95], v[96:97]
	v_add_f32_e32 v93, v100, v101
	v_add_f32_e32 v89, v89, v93
	v_add_f32_e32 v88, v88, v89
	v_mov_b32_e32 v89, v176
	s_and_b64 s[2:3], exec, s[40:41]
	v_lshlrev_b32_e32 v89, 2, v89
	v_bitop3_b32 v93, v89, s80, v178 bitop3:0x6c
	ds_bpermute_b32 v93, v93, v88
	s_or_b64 s[18:19], s[2:3], s[18:19]
	s_mov_b64 s[2:3], 0x800
	s_waitcnt lgkmcnt(0)
	v_add_f32_e32 v88, v88, v93
	v_bitop3_b32 v93, v89, 64, v178 bitop3:0x6c
	ds_bpermute_b32 v93, v93, v88
	s_waitcnt lgkmcnt(0)
	v_add_f32_e32 v88, v88, v93
	v_bitop3_b32 v93, v89, 32, v178 bitop3:0x6c
	ds_bpermute_b32 v93, v93, v88
	s_waitcnt lgkmcnt(0)
	v_add_f32_e32 v88, v88, v93
	v_bitop3_b32 v93, v89, 16, v178 bitop3:0x6c
	ds_bpermute_b32 v93, v93, v88
	s_waitcnt lgkmcnt(0)
	v_add_f32_e32 v88, v88, v93
	v_bitop3_b32 v93, v89, 8, v178 bitop3:0x6c
	ds_bpermute_b32 v93, v93, v88
	v_bitop3_b32 v89, v89, 4, v178 bitop3:0x6c
	s_waitcnt lgkmcnt(0)
	v_add_f32_e32 v88, v88, v93
	ds_bpermute_b32 v89, v89, v88
	s_waitcnt lgkmcnt(0)
	v_add_f32_e32 v88, v88, v89
	v_fmamk_f32 v88, v88, 0x3a800000, v90
	v_cmp_gt_f32_e32 vcc, s60, v88
	v_mul_f32_e32 v89, 0x4b800000, v88
	s_nop 0
	v_cndmask_b32_e32 v88, v88, v89, vcc
	v_rsq_f32_e32 v88, v88
	s_nop 0
	v_mul_f32_e32 v89, 0x45800000, v88
	v_cndmask_b32_e32 v88, v88, v89, vcc
	v_mul_f32_e32 v78, v78, v88
	v_mul_f32_e32 v78, v2, v78
	v_add_f32_e32 v89, 1.0, v26
	v_mul_f32_e32 v79, v79, v88
	v_fma_f32 v78, v89, v78, v58
	v_mul_f32_e32 v79, v3, v79
	v_add_f32_e32 v89, 1.0, v27
	v_mul_f32_e32 v80, v80, v88
	v_fma_f32 v79, v89, v79, v59
	v_mul_f32_e32 v80, v4, v80
	v_add_f32_e32 v89, 1.0, v28
	v_mul_f32_e32 v81, v81, v88
	v_fma_f32 v80, v89, v80, v60
	v_mul_f32_e32 v81, v5, v81
	v_add_f32_e32 v89, 1.0, v29
	v_cvt_pk_bf16_f32 v78, v78, v79
	v_mul_f32_e32 v74, v74, v88
	v_fma_f32 v81, v89, v81, v61
	v_cvt_pk_bf16_f32 v79, v80, v81
	global_store_dwordx2 v[84:85], v[78:79], off
	v_mul_f32_e32 v74, v6, v74
	v_add_f32_e32 v78, 1.0, v30
	v_mul_f32_e32 v75, v75, v88
	v_fma_f32 v74, v78, v74, v54
	v_mul_f32_e32 v75, v7, v75
	v_add_f32_e32 v78, 1.0, v31
	v_mul_f32_e32 v76, v76, v88
	v_fma_f32 v75, v78, v75, v55
	v_mul_f32_e32 v76, v8, v76
	v_add_f32_e32 v78, 1.0, v32
	v_mul_f32_e32 v77, v77, v88
	v_fma_f32 v76, v78, v76, v56
	v_mul_f32_e32 v77, v9, v77
	v_add_f32_e32 v78, 1.0, v33
	v_cvt_pk_bf16_f32 v74, v74, v75
	v_mul_f32_e32 v62, v62, v88
	v_fma_f32 v77, v78, v77, v57
	v_cvt_pk_bf16_f32 v75, v76, v77
	global_store_dwordx2 v[84:85], v[74:75], off offset:512
	v_mul_f32_e32 v62, v10, v62
	v_add_f32_e32 v74, 1.0, v34
	v_mul_f32_e32 v63, v63, v88
	v_fma_f32 v62, v74, v62, v70
	v_mul_f32_e32 v63, v11, v63
	v_add_f32_e32 v74, 1.0, v35
	v_mul_f32_e32 v64, v64, v88
	v_fma_f32 v63, v74, v63, v71
	v_mul_f32_e32 v64, v12, v64
	v_add_f32_e32 v74, 1.0, v36
	v_mul_f32_e32 v65, v65, v88
	v_fma_f32 v64, v74, v64, v72
	v_mul_f32_e32 v65, v13, v65
	v_add_f32_e32 v74, 1.0, v37
	v_cvt_pk_bf16_f32 v62, v62, v63
	v_mul_f32_e32 v18, v18, v88
	v_fma_f32 v65, v74, v65, v73
	v_cvt_pk_bf16_f32 v63, v64, v65
	global_store_dwordx2 v[84:85], v[62:63], off offset:1024
	v_mul_f32_e32 v18, v14, v18
	v_add_f32_e32 v62, 1.0, v38
	v_mul_f32_e32 v19, v19, v88
	v_fma_f32 v18, v62, v18, v66
	v_mul_f32_e32 v19, v15, v19
	v_add_f32_e32 v62, 1.0, v39
	v_mul_f32_e32 v20, v20, v88
	v_fma_f32 v19, v62, v19, v67
	v_mul_f32_e32 v20, v16, v20
	v_add_f32_e32 v62, 1.0, v40
	v_mul_f32_e32 v21, v21, v88
	v_fma_f32 v20, v62, v20, v68
	v_mul_f32_e32 v21, v17, v21
	v_add_f32_e32 v62, 1.0, v41
	v_fma_f32 v21, v62, v21, v69
	v_cvt_pk_bf16_f32 v18, v18, v19
	v_cvt_pk_bf16_f32 v19, v20, v21
	global_store_dwordx2 v[84:85], v[18:19], off offset:1536
	v_lshl_add_u64 v[84:85], v[84:85], 0, s[2:3]
	s_waitcnt vmcnt(4)
	v_mov_b64_e32 v[88:89], v[86:87]
	v_mov_b32_e32 v78, v50
	v_mov_b32_e32 v79, v51
	v_mov_b32_e32 v80, v52
	v_mov_b32_e32 v81, v53
	v_mov_b32_e32 v74, v46
	v_mov_b32_e32 v75, v47
	v_mov_b32_e32 v76, v48
	v_mov_b32_e32 v77, v49
	v_mov_b32_e32 v62, v42
	v_mov_b32_e32 v63, v43
	v_mov_b32_e32 v64, v44
	v_mov_b32_e32 v65, v45
	v_mov_b32_e32 v18, v22
	v_mov_b32_e32 v19, v23
	v_mov_b32_e32 v20, v24
	v_mov_b32_e32 v21, v25
	s_andn2_b64 exec, exec, s[18:19]
	s_cbranch_execz .LBB0_73

; DI void phase_rowpass(unsigned char* ws, int nrows, const float* xin_lat, const float* xin_ctx, const float* y, const float* gate_base  ,
;                       const float* gpost, bool write_x, bool write_h, const float* hmod_base  , int sc_which, int sh_which, const float* gpre) {
;     ...
;         if (mi != mi_cur) {
;             mi_cur = mi;
; #pragma unroll
;             for (int i = 0; i < 4; ++i) {
;                 if (y) vgt[i] = *(const f32x4*)(gate_base + (size_t)mi * 6144 + i * 256 + lane * 4);
;                 if (write_h) { vsc[i] = *(const f32x4*)(hmod_base + ((size_t)mi * 6 + sc_which) * 1024 + i * 256 + lane * 4);
;                                vsh[i] = *(const f32x4*)(hmod_base + ((size_t)mi * 6 + sh_which) * 1024 + i * 256 + lane * 4); }
;             }
.LBB0_67:
	s_or_b64 exec, exec, s[42:43]
	v_min_i32_e32 v88, 0x8000, v88
	v_ashrrev_i32_e32 v88, 12, v88
	v_cmp_ne_u32_e32 vcc, v88, v92
	s_and_saveexec_b64 s[42:43], vcc
	s_cbranch_execz .LBB0_64
	v_mul_i32_i24_e32 v26, 6, v88
	v_ashrrev_i32_e32 v27, 31, v26
	v_lshlrev_b64 v[26:27], 12, v[26:27]
	v_lshl_add_u64 v[66:67], v[82:83], 0, v[26:27]
	v_add_co_u32_e32 v38, vcc, 0x1000, v66
	v_mov_b32_e32 v92, v88
	s_nop 0
	v_addc_co_u32_e32 v39, vcc, 0, v67, vcc
	global_load_dwordx4 v[26:29], v[38:39], off
	global_load_dwordx4 v[30:33], v[38:39], off offset:1024
	global_load_dwordx4 v[58:61], v[66:67], off
	global_load_dwordx4 v[54:57], v[66:67], off offset:1024
	global_load_dwordx4 v[34:37], v[38:39], off offset:2048
	s_nop 0
	global_load_dwordx4 v[38:41], v[38:39], off offset:3072
	s_nop 0
	global_load_dwordx4 v[70:73], v[66:67], off offset:2048
	s_nop 0
	global_load_dwordx4 v[66:69], v[66:67], off offset:3072
	s_waitcnt vmcnt(0)
	s_branch .LBB0_64

; DI void phase_rowpass(unsigned char* ws, int nrows, const float* xin_lat, const float* xin_ctx, const float* y, const float* gate_base  ,
;                       const float* gpost, bool write_x, bool write_h, const float* hmod_base  , int sc_which, int sh_which, const float* gpre) {
;     ...
;         if (y) {
;             float ss = 0.f;
; #pragma unroll
;             for (int i = 0; i < 4; ++i) ss += yv[i][0] * yv[i][0] + yv[i][1] * yv[i][1] + yv[i][2] * yv[i][2] + yv[i][3] * yv[i][3];
;             ss = wave_sum(ss);
;             const float rs = rsqrtf(ss * (1.f / 1024.f) + eps);
; #pragma unroll
;             for (int i = 0; i < 4; ++i)
; #pragma unroll
;                 for (int j = 0; j < 4; ++j) xv[i][j] += vgt[i][j] * (yv[i][j] * rs * vgp[i][j]);
;         }
;         if (write_x) {
;             float* xo = r < ML ? xout_lat + (size_t)r * 1024 : xout_ctx + (size_t)(r - ML) * 1024;
; #pragma unroll
;             for (int i = 0; i < 4; ++i) __builtin_nontemporal_store(xv[i], (f32x4*)(xo + i * 256 + lane * 4));
;         }
;         if (write_h) {
;             float ss = 0.f;
; #pragma unroll
;             for (int i = 0; i < 4; ++i) ss += xv[i][0] * xv[i][0] + xv[i][1] * xv[i][1] + xv[i][2] * xv[i][2] + xv[i][3] * xv[i][3];
;             ss = wave_sum(ss);
;             const float rs = rsqrtf(ss * (1.f / 1024.f) + eps);
.LBB0_104:
	s_or_b64 exec, exec, s[20:21]
	s_waitcnt lgkmcnt(0)
	v_add_f32_e32 v166, v166, v167
	v_fmamk_f32 v166, v166, 0x3a800000, v141
	v_cmp_gt_f32_e32 vcc, s60, v166
	v_mul_f32_e32 v167, 0x4b800000, v166
	v_mov_b32_e32 v169, v128
	v_cndmask_b32_e32 v166, v166, v167, vcc
	v_rsq_f32_e32 v166, v166
	v_mov_b32_e32 v128, v133
	v_mov_b32_e32 v168, v132
	s_nop 0
	v_mov_b32_e32 v132, v53
	v_mul_f32_e32 v167, 0x45800000, v166
	v_cndmask_b32_e32 v166, v166, v167, vcc
	v_pk_mul_f32 v[128:129], v[128:129], v[166:167] op_sel_hi:[1,0]
	v_mov_b32_e32 v133, v57
	v_pk_mul_f32 v[128:129], v[16:17], v[128:129]
	v_pk_mul_f32 v[116:117], v[116:117], v[166:167] op_sel_hi:[1,0]
	v_pk_fma_f32 v[128:129], v[132:133], v[128:129], v[160:161]
	v_mov_b32_e32 v132, v134
	v_mov_b32_e32 v133, v130
	v_pk_mul_f32 v[132:133], v[132:133], v[166:167] op_sel_hi:[1,0]
	v_mov_b32_e32 v130, v135
	v_pk_mul_f32 v[132:133], v[14:15], v[132:133]
	v_mov_b32_e32 v160, v54
	v_mov_b32_e32 v161, v58
	v_pk_mul_f32 v[130:131], v[130:131], v[166:167] op_sel_hi:[1,0]
	v_pk_fma_f32 v[126:127], v[160:161], v[132:133], v[126:127]
	v_pk_mul_f32 v[130:131], v[4:5], v[130:131]
	v_mov_b32_e32 v132, v55
	v_mov_b32_e32 v133, v59
	v_pk_fma_f32 v[130:131], v[132:133], v[130:131], v[156:157]
	v_pk_mul_f32 v[132:133], v[162:163], v[166:167] op_sel_hi:[1,0]
	v_mov_b32_e32 v134, v80
	v_pk_mul_f32 v[132:133], v[10:11], v[132:133]
	v_mov_b32_e32 v135, v76
	v_pk_fma_f32 v[132:133], v[134:135], v[132:133], v[158:159]
	v_pk_mul_f32 v[116:117], v[8:9], v[116:117]
	v_mov_b32_e32 v134, v81
	v_mov_b32_e32 v135, v77
	v_pk_fma_f32 v[120:121], v[134:135], v[116:117], v[120:121]
	v_pk_mul_f32 v[116:117], v[136:137], v[166:167] op_sel_hi:[1,0]
	v_pk_mul_f32 v[168:169], v[168:169], v[166:167] op_sel_hi:[1,0]
	v_pk_mul_f32 v[116:117], v[6:7], v[116:117]
	v_mov_b32_e32 v134, v82
	v_mov_b32_e32 v135, v78
	v_pk_mul_f32 v[168:169], v[18:19], v[168:169]
	v_mov_b32_e32 v170, v52
	v_mov_b32_e32 v171, v56
	v_pk_fma_f32 v[134:135], v[134:135], v[116:117], v[154:155]
	v_pk_mul_f32 v[116:117], v[118:119], v[166:167] op_sel_hi:[1,0]
	v_pk_fma_f32 v[124:125], v[170:171], v[168:169], v[124:125]
	v_pk_mul_f32 v[116:117], v[2:3], v[116:117]
	v_mov_b32_e32 v118, v83
	v_mov_b32_e32 v119, v79
	v_pk_fma_f32 v[122:123], v[118:119], v[116:117], v[122:123]
	v_lshl_add_u64 v[136:137], v[138:139], 0, v[0:1]
	v_mov_b32_e32 v116, v124
	v_mov_b32_e32 v117, v128
	v_mov_b32_e32 v118, v126
	v_mov_b32_e32 v119, v130
	global_store_dwordx4 v[136:137], v[116:119], off nt
	s_and_b64 s[2:3], exec, s[40:41]
	s_or_b64 s[44:45], s[2:3], s[44:45]
	v_mov_b32_e32 v116, v125
	v_mov_b32_e32 v117, v129
	v_mov_b32_e32 v118, v127
	v_mov_b32_e32 v119, v131
	global_store_dwordx4 v[136:137], v[116:119], off offset:1024 nt
	s_add_u32 s18, s18, 0x1000
	s_mov_b64 s[2:3], 0x1000
	v_mov_b32_e32 v116, v133
	v_mov_b32_e32 v117, v121
	v_mov_b32_e32 v118, v135
	v_mov_b32_e32 v119, v123
	global_store_dwordx4 v[136:137], v[116:119], off offset:2048 nt
	s_addc_u32 s19, s19, 0
	v_lshl_add_u64 v[152:153], v[152:153], 0, s[2:3]
	v_mov_b32_e32 v116, v132
	v_mov_b32_e32 v117, v120
	v_mov_b32_e32 v118, v134
	v_mov_b32_e32 v119, v122
	global_store_dwordx4 v[136:137], v[116:119], off offset:3072 nt
	s_nop 1
	v_pk_mul_f32 v[116:117], v[128:129], v[128:129]
	v_pk_mul_f32 v[118:119], v[120:121], v[120:121]
	v_pk_fma_f32 v[116:117], v[124:125], v[124:125], v[116:117]
	v_pk_fma_f32 v[118:119], v[132:133], v[132:133], v[118:119]
	v_pk_fma_f32 v[116:117], v[126:127], v[126:127], v[116:117]
	v_pk_fma_f32 v[118:119], v[134:135], v[134:135], v[118:119]
	v_pk_fma_f32 v[116:117], v[130:131], v[130:131], v[116:117]
	v_pk_fma_f32 v[118:119], v[122:123], v[122:123], v[118:119]
	v_add_f32_e32 v0, v116, v117
	v_mov_b32_e32 v116, v176
	v_add_f32_e32 v0, v119, v0
	v_lshlrev_b32_e32 v116, 2, v116
	v_add_f32_e32 v0, v118, v0
	v_bitop3_b32 v117, v116, s80, v178 bitop3:0x6c
	ds_bpermute_b32 v117, v117, v0
	v_add_f32_e32 v119, 1.0, v88
	s_waitcnt lgkmcnt(0)
	v_add_f32_e32 v0, v0, v117
	v_bitop3_b32 v117, v116, 64, v178 bitop3:0x6c
	ds_bpermute_b32 v117, v117, v0
	s_waitcnt lgkmcnt(0)
	v_add_f32_e32 v0, v0, v117
	v_bitop3_b32 v117, v116, 32, v178 bitop3:0x6c
	ds_bpermute_b32 v117, v117, v0
	s_waitcnt lgkmcnt(0)
	v_add_f32_e32 v0, v0, v117
	v_bitop3_b32 v117, v116, 16, v178 bitop3:0x6c
	ds_bpermute_b32 v117, v117, v0
	s_waitcnt lgkmcnt(0)
	v_add_f32_e32 v0, v0, v117
	v_bitop3_b32 v117, v116, 8, v178 bitop3:0x6c
	ds_bpermute_b32 v117, v117, v0
	v_bitop3_b32 v116, v116, 4, v178 bitop3:0x6c
	s_waitcnt lgkmcnt(0)
	v_add_f32_e32 v0, v0, v117
	ds_bpermute_b32 v116, v116, v0
	s_waitcnt lgkmcnt(0)
; DI unsigned pk_bf16(float lo, float hi) { unsigned r; asm("v_cvt_pk_bf16_f32 %0, %1, %2" : "=v"(r) : "v"(lo), "v"(hi)); return r; }
; DI void phase_rowpass(unsigned char* ws, int nrows, const float* xin_lat, const float* xin_ctx, const float* y, const float* gate_base  ,
;                       const float* gpost, bool write_x, bool write_h, const float* hmod_base  , int sc_which, int sh_which, const float* gpre) {
;     ...
;     for (; r < rend; ++r) {
;         const int mi = r < ML ? (r >> 12) : 8;
;         const int rn = r + 1;
;         if (rn < rend) {
;             const float* xi = rn < ML ? xin_lat + (size_t)rn * 1024 : xin_ctx + (size_t)(rn - ML) * 1024;
; #pragma unroll
;             for (int i = 0; i < 4; ++i) xnx[i] = __builtin_nontemporal_load((const f32x4*)(xi + i * 256 + lane * 4));
;             if (y) {
; #pragma unroll
;                 for (int i = 0; i < 4; ++i) ynx[i] = __builtin_nontemporal_load((const f32x4*)(y + (size_t)rn * 1024 + i * 256 + lane * 4));
;             }
;         }
;         if (mi != mi_cur) {
;             mi_cur = mi;
; #pragma unroll
;             for (int i = 0; i < 4; ++i) {
;                 if (y) vgt[i] = *(const f32x4*)(gate_base + (size_t)mi * 6144 + i * 256 + lane * 4);
;                 if (write_h) { vsc[i] = *(const f32x4*)(hmod_base + ((size_t)mi * 6 + sc_which) * 1024 + i * 256 + lane * 4);
;                                vsh[i] = *(const f32x4*)(hmod_base + ((size_t)mi * 6 + sh_which) * 1024 + i * 256 + lane * 4); }
;             }
;         }
;     ...
; #pragma unroll
;             for (int i = 0; i < 4; ++i) {
;                 float hv[4];
; #pragma unroll
;                 for (int j = 0; j < 4; ++j) hv[j] = (xv[i][j] * rs * vpre[i][j]) * (1.f + vsc[i][j]) + vsh[i][j];
;                 u32x2 o; o[0] = pk_bf16(hv[0], hv[1]); o[1] = pk_bf16(hv[2], hv[3]);
;                 *(u32x2*)(H + (size_t)r * 1024 + i * 256 + lane * 4) = o;
;             }
;         }
; #pragma unroll
;         for (int i = 0; i < 4; ++i) { xv[i] = xnx[i]; yv[i] = ynx[i]; }
	v_add_f32_e32 v0, v0, v116
	v_fmamk_f32 v0, v0, 0x3a800000, v141
	v_cmp_gt_f32_e32 vcc, s60, v0
	v_mul_f32_e32 v116, 0x4b800000, v0
	s_nop 0
	v_cndmask_b32_e32 v0, v0, v116, vcc
	v_rsq_f32_e32 v0, v0
	s_nop 0
	v_mul_f32_e32 v116, 0x45800000, v0
	v_cndmask_b32_e32 v0, v0, v116, vcc
	v_mul_f32_e32 v118, v124, v0
	v_mul_f32_e32 v118, v20, v118
	v_fma_f32 v118, v119, v118, v104
	v_mul_f32_e32 v119, v128, v0
	v_mul_f32_e32 v119, v21, v119
	v_add_f32_e32 v124, 1.0, v89
	v_fma_f32 v119, v124, v119, v105
	v_mul_f32_e32 v124, v126, v0
	v_mul_f32_e32 v124, v22, v124
	v_add_f32_e32 v126, 1.0, v90
	v_lshlrev_b64 v[116:117], 11, v[144:145]
	v_fma_f32 v124, v126, v124, v106
	v_mul_f32_e32 v126, v130, v0
	v_lshl_add_u64 v[116:117], v[150:151], 0, v[116:117]
	v_mul_f32_e32 v126, v23, v126
	v_add_f32_e32 v128, 1.0, v91
	v_cvt_pk_bf16_f32 v118, v118, v119
	v_fma_f32 v126, v128, v126, v107
	v_cvt_pk_bf16_f32 v119, v124, v126
	global_store_dwordx2 v[116:117], v[118:119], off
	v_mul_f32_e32 v118, v125, v0
	v_mul_f32_e32 v118, v24, v118
	v_add_f32_e32 v119, 1.0, v84
	v_fma_f32 v118, v119, v118, v100
	v_mul_f32_e32 v119, v129, v0
	v_mul_f32_e32 v119, v25, v119
	v_add_f32_e32 v124, 1.0, v85
	v_fma_f32 v119, v124, v119, v101
	v_mul_f32_e32 v124, v127, v0
	v_mul_f32_e32 v124, v26, v124
	v_add_f32_e32 v125, 1.0, v86
	v_fma_f32 v124, v125, v124, v102
	v_mul_f32_e32 v125, v131, v0
	v_mul_f32_e32 v125, v27, v125
	v_add_f32_e32 v126, 1.0, v87
	v_cvt_pk_bf16_f32 v118, v118, v119
	v_fma_f32 v125, v126, v125, v103
	v_cvt_pk_bf16_f32 v119, v124, v125
	global_store_dwordx2 v[116:117], v[118:119], off offset:512
	v_mul_f32_e32 v118, v133, v0
	v_mul_f32_e32 v118, v28, v118
	v_add_f32_e32 v119, 1.0, v96
	v_fma_f32 v118, v119, v118, v112
	v_mul_f32_e32 v119, v121, v0
	v_mul_f32_e32 v119, v29, v119
	v_add_f32_e32 v121, 1.0, v97
	v_fma_f32 v119, v121, v119, v113
	v_mul_f32_e32 v121, v135, v0
	v_mul_f32_e32 v121, v30, v121
	v_add_f32_e32 v124, 1.0, v98
	v_mul_f32_e32 v123, v123, v0
	v_fma_f32 v121, v124, v121, v114
	v_mul_f32_e32 v123, v31, v123
	v_add_f32_e32 v124, 1.0, v99
	v_cvt_pk_bf16_f32 v118, v118, v119
	v_fma_f32 v123, v124, v123, v115
	v_cvt_pk_bf16_f32 v119, v121, v123
	global_store_dwordx2 v[116:117], v[118:119], off offset:1024
	v_mul_f32_e32 v118, v132, v0
	v_mul_f32_e32 v118, v32, v118
	v_add_f32_e32 v119, 1.0, v92
	v_fma_f32 v118, v119, v118, v108
	v_mul_f32_e32 v119, v120, v0
	v_mul_f32_e32 v119, v33, v119
	v_add_f32_e32 v120, 1.0, v93
	v_fma_f32 v119, v120, v119, v109
	v_mul_f32_e32 v120, v134, v0
	v_mul_f32_e32 v120, v34, v120
	v_add_f32_e32 v121, 1.0, v94
	v_mul_f32_e32 v0, v122, v0
	v_fma_f32 v120, v121, v120, v110
	v_mul_f32_e32 v0, v35, v0
	v_add_f32_e32 v121, 1.0, v95
	v_fma_f32 v0, v121, v0, v111
	v_cvt_pk_bf16_f32 v118, v118, v119
	v_cvt_pk_bf16_f32 v119, v120, v0
	global_store_dwordx2 v[116:117], v[118:119], off offset:1536
	s_waitcnt vmcnt(8)
	v_mov_b64_e32 v[138:139], v[62:63]
	v_mov_b64_e32 v[136:137], v[60:61]
	v_mov_b32_e32 v160, v49
	v_mov_b32_e32 v156, v51
	v_mov_b32_e32 v161, v45
	v_mov_b32_e32 v157, v47
	v_mov_b32_e32 v159, v40
	v_mov_b32_e32 v155, v42
	v_mov_b32_e32 v158, v36
	v_mov_b32_e32 v154, v38
	v_mov_b64_e32 v[118:119], v[66:67]
	v_mov_b64_e32 v[130:131], v[70:71]
	v_mov_b64_e32 v[134:135], v[74:75]
	v_mov_b64_e32 v[144:145], v[12:13]
	v_mov_b64_e32 v[116:117], v[64:65]
	v_mov_b64_e32 v[128:129], v[68:69]
	v_mov_b64_e32 v[132:133], v[72:73]
	v_mov_b32_e32 v124, v48
	v_mov_b32_e32 v126, v50
	v_mov_b32_e32 v125, v44
	v_mov_b32_e32 v127, v46
	v_mov_b32_e32 v121, v41
	v_mov_b32_e32 v123, v43
	v_mov_b32_e32 v120, v37
	v_mov_b32_e32 v122, v39
	s_andn2_b64 exec, exec, s[44:45]
	s_cbranch_execz .LBB0_113
.LBB0_105:
	v_lshl_add_u64 v[12:13], v[144:145], 0, 1
	v_cmp_lt_i32_e32 vcc, v12, v164
	v_cmp_ge_i32_e64 s[40:41], v12, v164
	v_lshlrev_b32_e32 v0, 2, v140
	s_and_saveexec_b64 s[46:47], vcc
	s_cbranch_execz .LBB0_107
	v_add_u32_e32 v36, 0xffff8001, v144
	v_cmp_gt_i32_e32 vcc, s67, v144
	v_mov_b32_e32 v38, s17
	v_mov_b32_e32 v39, s15
	v_cndmask_b32_e32 v37, 0, v13, vcc
	v_cndmask_b32_e32 v36, v36, v12, vcc
	v_cndmask_b32_e32 v39, v38, v39, vcc
	v_mov_b32_e32 v38, s16
	v_mov_b32_e32 v40, s14
	v_cndmask_b32_e32 v38, v38, v40, vcc
	v_lshlrev_b64 v[36:37], 12, v[36:37]
	v_lshl_add_u64 v[60:61], v[152:153], 0, v[142:143]
	v_lshl_add_u64 v[36:37], v[38:39], 0, v[36:37]
	v_add_co_u32_e32 v60, vcc, 0xb0e3000, v60
	v_lshl_add_u64 v[36:37], v[36:37], 0, v[0:1]
	s_nop 0
	v_addc_co_u32_e32 v61, vcc, 0, v61, vcc
	global_load_dwordx4 v[48:51], v[36:37], off nt
	global_load_dwordx4 v[44:47], v[36:37], off offset:1024 nt
	global_load_dwordx4 v[40:43], v[36:37], off offset:2048 nt
	s_nop 0
	global_load_dwordx4 v[36:39], v[36:37], off offset:3072 nt
	s_nop 0
	global_load_dwordx4 v[72:75], v[60:61], off nt
	global_load_dwordx4 v[68:71], v[60:61], off offset:1024 nt
	global_load_dwordx4 v[64:67], v[60:61], off offset:2048 nt
	s_nop 0
	global_load_dwordx4 v[60:63], v[60:61], off offset:3072 nt
.LBB0_107:
	s_or_b64 exec, exec, s[46:47]
	v_min_i32_e32 v162, 0x8000, v144
	v_ashrrev_i32_e32 v162, 12, v162
	v_cmp_ne_u32_e32 vcc, v162, v165
	s_and_saveexec_b64 s[46:47], vcc
	s_cbranch_execz .LBB0_109
	v_mul_hi_i32_i24_e32 v53, 0x6000, v162
	v_mul_i32_i24_e32 v52, 0x6000, v162
	v_lshl_add_u64 v[80:81], v[148:149], 0, v[52:53]
	v_mul_i32_i24_e32 v52, 6, v162
	v_ashrrev_i32_e32 v53, 31, v52
	v_lshlrev_b64 v[52:53], 12, v[52:53]
	v_lshl_add_u64 v[52:53], v[146:147], 0, v[52:53]
	v_add_co_u32_e32 v92, vcc, 0x4000, v52
	v_mov_b32_e32 v165, v162
	s_nop 0
	v_addc_co_u32_e32 v93, vcc, 0, v53, vcc
	v_add_co_u32_e32 v108, vcc, 0x3000, v52
	s_nop 1
	v_addc_co_u32_e32 v109, vcc, 0, v53, vcc
	global_load_dwordx4 v[52:55], v[80:81], off
	global_load_dwordx4 v[56:59], v[80:81], off offset:1024
	global_load_dwordx4 v[88:91], v[92:93], off
	global_load_dwordx4 v[84:87], v[92:93], off offset:1024
	global_load_dwordx4 v[104:107], v[108:109], off
	global_load_dwordx4 v[100:103], v[108:109], off offset:1024
	global_load_dwordx4 v[76:79], v[80:81], off offset:2048
	s_nop 0
	global_load_dwordx4 v[80:83], v[80:81], off offset:3072
	s_nop 0
	global_load_dwordx4 v[96:99], v[92:93], off offset:2048
	s_nop 0
	global_load_dwordx4 v[92:95], v[92:93], off offset:3072
	s_nop 0
	global_load_dwordx4 v[112:115], v[108:109], off offset:2048
	s_nop 0
	global_load_dwordx4 v[108:111], v[108:109], off offset:3072
	s_waitcnt vmcnt(0)

; DI float lo_f(unsigned w) { return __uint_as_float(w << 16); }
; DI float hi_f(unsigned w) { return __uint_as_float(w & 0xffff0000u); }
; DI void attn_item(const bf16_t* P, bf16_t* Y, const float* sinkp, const float* rope, unsigned char* lds, bool is_ctx, int b, int blk, int hp) {
;     ...
;     ATT_LOAD(sp0);
;     bf16x8 Qf0[2], Qf1[2];
; #pragma unroll
;     for (int t = 0; t < 2; ++t) {
;         const int qi = qi0 + 16 * t, tq = blk * 128 + qi;
;         const bf16_t* qp = P + (qrow0 + qi) * IN_DIM + C_AQ + h * 64 + fq * 8;
;         const u32x4 q0 = *(const u32x4*)qp, q1 = *(const u32x4*)(qp + 32);
;         float qa[8], qb[8];
; #pragma unroll
;         for (int j = 0; j < 4; ++j) { qa[2 * j] = lo_f(q0[j]); qa[2 * j + 1] = hi_f(q0[j]); qb[2 * j] = lo_f(q1[j]); qb[2 * j + 1] = hi_f(q1[j]); }
;         if (!is_ctx) {
;             const int pos = fq < 2 ? (tq >> 6) : (tq & 63);
;             const float* rt = rope + (pos * 16 + (fq & 1) * 8) * 2;
; #pragma unroll
;             for (int j = 0; j < 8; ++j) { const float c = rt[2 * j], s = rt[2 * j + 1]; const float a = qa[j], bb = qb[j]; qa[j] = a * c - bb * s; qb[j] = a * s + bb * c; }
;         }
;     ...
;     {   const float sk = sinkp[h] * 1.4426950408889634f;
.LBB0_481:
	s_lshl_b32 s4, s4, 7
	v_lshrrev_b32_e32 v0, 1, v62
	v_ashrrev_i32_e32 v147, 31, v146
	s_or_b32 s48, s48, s4
	v_and_b32_e32 v34, 0x60, v0
	s_and_b32 s4, s3, 3
	v_ashrrev_i32_e32 v0, 8, v62
	v_lshl_add_u64 v[18:19], s[50:51], 0, v[146:147]
	v_mov_b64_e32 v[20:21], s[76:77]
	v_lshl_add_u32 v52, s4, 1, v0
	v_mad_u64_u32 v[20:21], s[4:5], v18, s28, v[20:21]
	v_mov_b32_e32 v0, v21
	s_lshl_b32 s3, s3, 5
	v_mad_u64_u32 v[18:19], s[4:5], v19, s28, v[0:1]
	s_and_b32 s3, s3, 64
	v_mov_b32_e32 v21, v18
	s_lshl_b32 s72, s3, 1
	v_lshlrev_b32_e32 v150, 6, v52
	v_and_b32_e32 v64, 15, v62
	v_lshl_add_u64 v[18:19], v[20:21], 0, s[72:73]
	v_lshlrev_b32_e32 v0, 4, v63
	v_ashrrev_i32_e32 v151, 31, v150
	v_or_b32_e32 v50, v34, v64
	v_lshl_add_u64 v[30:31], v[18:19], 0, v[0:1]
	v_lshl_add_u64 v[18:19], v[150:151], 1, s[76:77]
	v_and_b32_e32 v0, 48, v62
	v_mov_b32_e32 v51, v1
	v_lshl_add_u64 v[42:43], v[18:19], 0, v[0:1]
	v_lshl_add_u64 v[148:149], s[48:49], 0, v[50:51]
	v_mad_u64_u32 v[18:19], s[4:5], v148, s28, v[42:43]
	v_mov_b32_e32 v0, v19
	v_mad_u64_u32 v[20:21], s[4:5], v149, s28, v[0:1]
	v_mov_b32_e32 v19, v20
	flat_load_dwordx4 v[44:47], v[18:19]
	flat_load_dwordx4 v[56:59], v[18:19] offset:64
	s_nop 0
	flat_load_dwordx4 v[18:21], v[30:31] offset:1024
	flat_load_dwordx4 v[22:25], v[30:31] offset:1088
	flat_load_dwordx4 v[26:29], v[30:31] offset:1280
	s_nop 0
	flat_load_dwordx4 v[30:33], v[30:31] offset:1344
	v_and_b32_e32 v51, 63, v62
	v_and_b32_e32 v0, 16, v62
	v_lshl_or_b32 v34, s24, 7, v34
	s_and_b64 vcc, exec, s[40:41]
	v_cmp_gt_u32_e64 s[42:43], 32, v51
	v_lshrrev_b32_e32 v53, 6, v34
	v_lshlrev_b32_e32 v65, 2, v0
	v_or_b32_e32 v124, 16, v50
	v_mov_b32_e32 v125, v1
	v_lshl_add_u64 v[126:127], s[48:49], 0, v[124:125]
	v_mad_u64_u32 v[128:129], s[4:5], v126, s28, v[42:43]
	v_mov_b32_e32 v131, v1
	v_mov_b32_e32 v130, v129
	v_mad_u64_u32 v[130:131], s[4:5], v127, s28, v[130:131]
	v_and_b32_e32 v132, 47, v50
	v_mov_b32_e32 v129, v130
	v_cndmask_b32_e64 v132, v132, v53, s[42:43]
	global_load_dwordx4 v[82:85], v[128:129], off
	global_load_dwordx4 v[86:89], v[128:129], off offset:64
	v_lshl_or_b32 v132, v132, 7, v65
	v_mov_b32_e32 v133, v1
	v_lshl_add_u64 v[126:127], s[8:9], 0, v[132:133]
	v_and_b32_e32 v124, 63, v124
	global_load_dwordx4 v[90:93], v[126:127], off
	global_load_dwordx4 v[94:97], v[126:127], off offset:16
	global_load_dwordx4 v[98:101], v[126:127], off offset:32
	global_load_dwordx4 v[102:105], v[126:127], off offset:48
	v_cndmask_b32_e64 v124, v124, v53, s[42:43]
	v_lshl_or_b32 v124, v124, 7, v65
	v_lshl_add_u64 v[126:127], s[8:9], 0, v[124:125]
	global_load_dwordx4 v[106:109], v[126:127], off
	global_load_dwordx4 v[110:113], v[126:127], off offset:16
	global_load_dwordx4 v[114:117], v[126:127], off offset:32
	global_load_dwordx4 v[118:121], v[126:127], off offset:48
	s_waitcnt vmcnt(0) lgkmcnt(0)
	v_ashrrev_i32_e32 v125, 31, v52
	v_mov_b32_e32 v124, v52
	v_lshl_add_u64 v[126:127], v[124:125], 2, s[46:47]
	v_lshl_add_u64 v[126:127], s[16:17], 0, v[126:127]
	global_load_dword v122, v[126:127], off
	v_and_b32_e32 v34, 0xffff0000, v44
	v_lshlrev_b32_e32 v35, 16, v44
	v_and_b32_e32 v38, 0xffff0000, v56
	v_lshlrev_b32_e32 v39, 16, v56
	v_and_b32_e32 v54, 0xffff0000, v45
	v_lshlrev_b32_e32 v55, 16, v45
	v_and_b32_e32 v48, 0xffff0000, v57
	v_lshlrev_b32_e32 v49, 16, v57
	v_and_b32_e32 v36, 0xffff0000, v46
	v_lshlrev_b32_e32 v37, 16, v46
	v_and_b32_e32 v40, 0xffff0000, v58
	v_lshlrev_b32_e32 v41, 16, v58
	v_and_b32_e32 v46, 0xffff0000, v47
	v_lshlrev_b32_e32 v47, 16, v47
	v_and_b32_e32 v44, 0xffff0000, v59
	v_lshlrev_b32_e32 v45, 16, v59
	s_cbranch_vccnz .LBB0_483
	v_and_b32_e32 v0, 47, v50
	v_cndmask_b32_e64 v0, v0, v53, s[42:43]
	v_lshl_or_b32 v0, v0, 7, v65
	v_lshl_add_u64 v[60:61], s[8:9], 0, v[0:1]
	v_mov_b32_e32 v56, v90
	v_mov_b32_e32 v57, v91
	v_mov_b32_e32 v58, v92
	v_mov_b32_e32 v59, v93
	v_mov_b32_e32 v66, v59
	v_mov_b32_e32 v67, v57
	v_pk_mul_f32 v[68:69], v[66:67], v[34:35]
	v_mov_b32_e32 v59, v56
	v_pk_mul_f32 v[56:57], v[66:67], v[38:39]
	v_pk_fma_f32 v[38:39], v[58:59], v[38:39], v[68:69]
	v_pk_fma_f32 v[34:35], v[58:59], v[34:35], v[56:57] neg_lo:[0,0,1] neg_hi:[0,0,1]
	v_mov_b32_e32 v56, v94
	v_mov_b32_e32 v57, v95
	v_mov_b32_e32 v58, v96
	v_mov_b32_e32 v59, v97
	v_mov_b32_e32 v66, v59
	v_mov_b32_e32 v67, v57
	v_pk_mul_f32 v[68:69], v[66:67], v[54:55]
	v_mov_b32_e32 v59, v56
	v_pk_mul_f32 v[56:57], v[66:67], v[48:49]
	v_pk_fma_f32 v[48:49], v[58:59], v[48:49], v[68:69]
	v_pk_fma_f32 v[54:55], v[58:59], v[54:55], v[56:57] neg_lo:[0,0,1] neg_hi:[0,0,1]
	v_mov_b32_e32 v56, v98
	v_mov_b32_e32 v57, v99
	v_mov_b32_e32 v58, v100
	v_mov_b32_e32 v59, v101
	v_mov_b32_e32 v66, v59
	v_mov_b32_e32 v67, v57
	v_pk_mul_f32 v[68:69], v[66:67], v[36:37]
	v_mov_b32_e32 v59, v56
	v_pk_mul_f32 v[56:57], v[66:67], v[40:41]
	v_pk_fma_f32 v[40:41], v[58:59], v[40:41], v[68:69]
	v_pk_fma_f32 v[36:37], v[58:59], v[36:37], v[56:57] neg_lo:[0,0,1] neg_hi:[0,0,1]
	v_mov_b32_e32 v56, v102
	v_mov_b32_e32 v57, v103
	v_mov_b32_e32 v58, v104
	v_mov_b32_e32 v59, v105
	v_mov_b32_e32 v60, v59
	v_mov_b32_e32 v61, v57
	v_pk_mul_f32 v[66:67], v[60:61], v[46:47]
	v_mov_b32_e32 v59, v56
	v_pk_mul_f32 v[56:57], v[60:61], v[44:45]
	v_pk_fma_f32 v[44:45], v[58:59], v[44:45], v[66:67]
	v_pk_fma_f32 v[46:47], v[58:59], v[46:47], v[56:57] neg_lo:[0,0,1] neg_hi:[0,0,1]
; DI unsigned pk_bf16(float lo, float hi) { unsigned r; asm("v_cvt_pk_bf16_f32 %0, %1, %2" : "=v"(r) : "v"(lo), "v"(hi)); return r; }
; DI float lo_f(unsigned w) { return __uint_as_float(w << 16); }
; DI float hi_f(unsigned w) { return __uint_as_float(w & 0xffff0000u); }
; DI void attn_item(const bf16_t* P, bf16_t* Y, const float* sinkp, const float* rope, unsigned char* lds, bool is_ctx, int b, int blk, int hp) {
;     ...
;     for (int t = 0; t < 2; ++t) {
;         const int qi = qi0 + 16 * t, tq = blk * 128 + qi;
;         const bf16_t* qp = P + (qrow0 + qi) * IN_DIM + C_AQ + h * 64 + fq * 8;
;         const u32x4 q0 = *(const u32x4*)qp, q1 = *(const u32x4*)(qp + 32);
;         float qa[8], qb[8];
; #pragma unroll
;         for (int j = 0; j < 4; ++j) { qa[2 * j] = lo_f(q0[j]); qa[2 * j + 1] = hi_f(q0[j]); qb[2 * j] = lo_f(q1[j]); qb[2 * j + 1] = hi_f(q1[j]); }
;         if (!is_ctx) {
;             const int pos = fq < 2 ? (tq >> 6) : (tq & 63);
;             const float* rt = rope + (pos * 16 + (fq & 1) * 8) * 2;
; #pragma unroll
;             for (int j = 0; j < 8; ++j) { const float c = rt[2 * j], s = rt[2 * j + 1]; const float a = qa[j], bb = qb[j]; qa[j] = a * c - bb * s; qb[j] = a * s + bb * c; }
;         }
;         const float qs = 0.125f * 1.4426950408889634f;
;         u32x4 o0, o1;
; #pragma unroll
;         for (int j = 0; j < 4; ++j) { o0[j] = pk_bf16(qa[2 * j] * qs, qa[2 * j + 1] * qs); o1[j] = pk_bf16(qb[2 * j] * qs, qb[2 * j + 1] * qs); }
;         Qf0[t] = __builtin_bit_cast(bf16x8, o0); Qf1[t] = __builtin_bit_cast(bf16x8, o1);
;     }
;     float m_run[2], l_run[2];
;     f32x4 O[2][4];
;     {   const float sk = sinkp[h] * 1.4426950408889634f;
; #pragma unroll
;         for (int t = 0; t < 2; ++t) { m_run[t] = sk; l_run[t] = 1.f;
; #pragma unroll
;             for (int dt = 0; dt < 4; ++dt) O[t][dt] = (f32x4){0.f, 0.f, 0.f, 0.f}; } }
.LBB0_483:
	v_mul_f32_e32 v0, 0x3e38aa3b, v35
	v_mul_f32_e32 v34, 0x3e38aa3b, v34
	v_cvt_pk_bf16_f32 v34, v0, v34
	v_mul_f32_e32 v0, 0x3e38aa3b, v39
	v_mul_f32_e32 v35, 0x3e38aa3b, v38
	v_cvt_pk_bf16_f32 v38, v0, v35
	v_mul_f32_e32 v0, 0x3e38aa3b, v55
	v_mul_f32_e32 v35, 0x3e38aa3b, v54
	v_cvt_pk_bf16_f32 v35, v0, v35
	v_mul_f32_e32 v0, 0x3e38aa3b, v49
	v_mul_f32_e32 v39, 0x3e38aa3b, v48
	v_cvt_pk_bf16_f32 v39, v0, v39
	v_mul_f32_e32 v0, 0x3e38aa3b, v37
	v_mul_f32_e32 v36, 0x3e38aa3b, v36
	v_cvt_pk_bf16_f32 v36, v0, v36
	v_mul_f32_e32 v0, 0x3e38aa3b, v41
	v_mul_f32_e32 v37, 0x3e38aa3b, v40
	v_cvt_pk_bf16_f32 v40, v0, v37
	v_mul_f32_e32 v0, 0x3e38aa3b, v47
	v_mul_f32_e32 v37, 0x3e38aa3b, v46
	v_cvt_pk_bf16_f32 v37, v0, v37
	v_mul_f32_e32 v0, 0x3e38aa3b, v45
	v_mul_f32_e32 v41, 0x3e38aa3b, v44
	v_cvt_pk_bf16_f32 v41, v0, v41
	v_or_b32_e32 v0, 16, v50
	v_lshl_add_u64 v[44:45], s[48:49], 0, v[0:1]
	v_mad_u64_u32 v[42:43], s[4:5], v44, s28, v[42:43]
	v_mov_b32_e32 v44, v43
	v_mad_u64_u32 v[44:45], s[4:5], v45, s28, v[44:45]
	v_mov_b32_e32 v43, v44
	v_mov_b32_e32 v54, v82
	v_mov_b32_e32 v55, v83
	v_mov_b32_e32 v56, v84
	v_mov_b32_e32 v57, v85
	v_mov_b32_e32 v66, v86
	v_mov_b32_e32 v67, v87
	v_mov_b32_e32 v68, v88
	v_mov_b32_e32 v69, v89
	s_and_b64 vcc, exec, s[40:41]
	v_and_b32_e32 v42, 0xffff0000, v54
	v_lshlrev_b32_e32 v43, 16, v54
	v_and_b32_e32 v46, 0xffff0000, v66
	v_lshlrev_b32_e32 v47, 16, v66
	v_and_b32_e32 v60, 0xffff0000, v55
	v_lshlrev_b32_e32 v61, 16, v55
	v_and_b32_e32 v58, 0xffff0000, v67
	v_lshlrev_b32_e32 v59, 16, v67
	v_and_b32_e32 v44, 0xffff0000, v56
	v_lshlrev_b32_e32 v45, 16, v56
	v_and_b32_e32 v48, 0xffff0000, v68
	v_lshlrev_b32_e32 v49, 16, v68
	v_and_b32_e32 v56, 0xffff0000, v57
	v_lshlrev_b32_e32 v57, 16, v57
	v_and_b32_e32 v54, 0xffff0000, v69
	v_lshlrev_b32_e32 v55, 16, v69
	s_cbranch_vccnz .LBB0_485
	v_and_b32_e32 v0, 63, v0
	v_cndmask_b32_e64 v0, v0, v53, s[42:43]
	v_lshl_or_b32 v0, v0, 7, v65
	v_lshl_add_u64 v[70:71], s[8:9], 0, v[0:1]
	v_mov_b32_e32 v66, v106
	v_mov_b32_e32 v67, v107
	v_mov_b32_e32 v68, v108
	v_mov_b32_e32 v69, v109
	v_mov_b32_e32 v72, v69
	v_mov_b32_e32 v73, v67
	v_pk_mul_f32 v[74:75], v[72:73], v[42:43]
	v_mov_b32_e32 v69, v66
	v_pk_mul_f32 v[66:67], v[72:73], v[46:47]
	v_pk_fma_f32 v[46:47], v[68:69], v[46:47], v[74:75]
	v_pk_fma_f32 v[42:43], v[68:69], v[42:43], v[66:67] neg_lo:[0,0,1] neg_hi:[0,0,1]
	v_mov_b32_e32 v66, v110
	v_mov_b32_e32 v67, v111
	v_mov_b32_e32 v68, v112
	v_mov_b32_e32 v69, v113
	v_mov_b32_e32 v72, v69
	v_mov_b32_e32 v73, v67
	v_pk_mul_f32 v[74:75], v[72:73], v[60:61]
	v_mov_b32_e32 v69, v66
	v_pk_mul_f32 v[66:67], v[72:73], v[58:59]
	v_pk_fma_f32 v[58:59], v[68:69], v[58:59], v[74:75]
	v_pk_fma_f32 v[60:61], v[68:69], v[60:61], v[66:67] neg_lo:[0,0,1] neg_hi:[0,0,1]
	v_mov_b32_e32 v66, v114
	v_mov_b32_e32 v67, v115
	v_mov_b32_e32 v68, v116
	v_mov_b32_e32 v69, v117
	v_mov_b32_e32 v72, v69
	v_mov_b32_e32 v73, v67
	v_pk_mul_f32 v[74:75], v[72:73], v[44:45]
	v_mov_b32_e32 v69, v66
	v_pk_mul_f32 v[66:67], v[72:73], v[48:49]
	v_pk_fma_f32 v[48:49], v[68:69], v[48:49], v[74:75]
	v_pk_fma_f32 v[44:45], v[68:69], v[44:45], v[66:67] neg_lo:[0,0,1] neg_hi:[0,0,1]
	v_mov_b32_e32 v66, v118
	v_mov_b32_e32 v67, v119
	v_mov_b32_e32 v68, v120
	v_mov_b32_e32 v69, v121
	v_mov_b32_e32 v70, v69
	v_mov_b32_e32 v71, v67
	v_pk_mul_f32 v[72:73], v[70:71], v[56:57]
	v_mov_b32_e32 v69, v66
	v_pk_mul_f32 v[66:67], v[70:71], v[54:55]
	v_pk_fma_f32 v[54:55], v[68:69], v[54:55], v[72:73]
	v_pk_fma_f32 v[56:57], v[68:69], v[56:57], v[66:67] neg_lo:[0,0,1] neg_hi:[0,0,1]
.LBB0_485:
	s_and_b64 s[4:5], s[44:45], exec
	s_cselect_b32 s2, 2, s2
	s_cmp_eq_u32 s24, 31
	v_mul_f32_e32 v43, 0x3e38aa3b, v43
	v_mul_f32_e32 v42, 0x3e38aa3b, v42
	s_cselect_b64 s[4:5], -1, 0
	v_cvt_pk_bf16_f32 v42, v43, v42
	v_mul_f32_e32 v43, 0x3e38aa3b, v47
	v_mul_f32_e32 v46, 0x3e38aa3b, v46
	v_mul_f32_e32 v45, 0x3e38aa3b, v45
	v_mul_f32_e32 v44, 0x3e38aa3b, v44
	s_or_b64 s[4:5], s[44:45], s[4:5]
	v_cvt_pk_bf16_f32 v46, v43, v46
	v_mul_f32_e32 v43, 0x3e38aa3b, v61
	v_mul_f32_e32 v47, 0x3e38aa3b, v60
	v_cvt_pk_bf16_f32 v44, v45, v44
	v_mul_f32_e32 v45, 0x3e38aa3b, v49
	v_mul_f32_e32 v48, 0x3e38aa3b, v48
	s_and_b64 s[4:5], s[4:5], exec
	v_cvt_pk_bf16_f32 v43, v43, v47
	v_mul_f32_e32 v47, 0x3e38aa3b, v59
	v_mul_f32_e32 v53, 0x3e38aa3b, v58
	v_cvt_pk_bf16_f32 v48, v45, v48
	v_mul_f32_e32 v45, 0x3e38aa3b, v57
	v_mul_f32_e32 v49, 0x3e38aa3b, v56
	s_cselect_b32 s3, 4, 5
	s_add_u32 s40, s46, s16
	v_cvt_pk_bf16_f32 v47, v47, v53
	v_cvt_pk_bf16_f32 v45, v45, v49
	v_mul_f32_e32 v49, 0x3e38aa3b, v55
	v_mul_f32_e32 v53, 0x3e38aa3b, v54
	s_addc_u32 s41, s47, s17
	v_cvt_pk_bf16_f32 v49, v49, v53
	v_ashrrev_i32_e32 v53, 31, v52
	v_lshl_add_u64 v[52:53], v[52:53], 2, s[40:41]
	s_nop 0
	s_movk_i32 s4, 0x48
	v_bfe_u32 v0, v62, 4, 2
	v_lshlrev_b32_e32 v66, 3, v0
	v_lshlrev_b32_e32 v172, 2, v0
	v_lshlrev_b32_e32 v0, 2, v51
	v_xor_b32_e32 v174, 64, v0
	v_xor_b32_e32 v175, 0x80, v0
	v_lshrrev_b32_e32 v0, 2, v64
	v_lshlrev_b32_e32 v65, 3, v63
	v_sub_u32_e32 v173, v50, v172
	v_or_b32_e32 v0, v172, v0
	v_lshlrev_b32_e32 v50, 2, v62
	v_and_b32_e32 v50, 12, v50
	v_mul_u32_u24_e32 v188, 0x90, v0
	v_lshlrev_b32_e32 v0, 1, v65
	v_mov_b32_e32 v58, 0
	v_cmp_gt_u32_e64 s[40:41], 2, v63
	v_mul_u32_u24_e32 v186, 0x90, v64
	v_add_u32_e32 v187, 16, v173
	v_mov_b32_e32 v193, 1.0
	s_mov_b32 s35, 0
	v_lshlrev_b32_e32 v190, 1, v66
	v_lshlrev_b32_e32 v191, 1, v50
	v_mov_b32_e32 v164, 1.0
	v_mov_b32_e32 v59, v58
	v_mov_b32_e32 v60, v58
	v_mov_b32_e32 v61, v58
	v_mov_b32_e32 v62, v58
	v_mov_b32_e32 v63, v58
	v_mov_b32_e32 v64, v58
	v_mov_b32_e32 v65, v58
	v_mov_b32_e32 v54, v58
	v_mov_b32_e32 v55, v58
	v_mov_b32_e32 v56, v58
	v_mov_b32_e32 v57, v58
	v_mov_b32_e32 v50, v58
	v_mov_b32_e32 v51, v58
	v_mov_b32_e32 v53, v58
	v_mov_b32_e32 v78, v58
	v_mov_b32_e32 v79, v58
	v_mov_b32_e32 v80, v58
	v_mov_b32_e32 v81, v58
	v_mov_b32_e32 v74, v58
	v_mov_b32_e32 v75, v58
	v_mov_b32_e32 v76, v58
	v_mov_b32_e32 v77, v58
	v_mov_b32_e32 v70, v58
	v_mov_b32_e32 v71, v58
	v_mov_b32_e32 v72, v58
	v_mov_b32_e32 v73, v58
	v_mov_b32_e32 v66, v58
	v_mov_b32_e32 v67, v58
	v_mov_b32_e32 v68, v58
	v_mov_b32_e32 v69, v58
	s_movk_i32 s37, 0x62
	s_movk_i32 s50, 0x63
	s_movk_i32 s51, 0x70
	s_barrier
	s_waitcnt vmcnt(0)
	v_mul_f32_e32 v162, 0x3fb8aa3b, v122
	v_mul_lo_u32 v52, v146, s4
	s_lshl_b32 s4, s18, 8
	s_ashr_i32 s5, s4, 31
	s_add_u32 s4, s4, 0x8000
	s_addc_u32 s5, s5, 0
	s_ashr_i32 s19, s18, 31
	s_add_i32 s24, s24, -1
	s_lshl_b64 s[18:19], s[18:19], 12
	s_add_u32 s6, s76, s72
	s_addc_u32 s7, s77, 0
	v_lshl_add_u64 v[152:153], s[6:7], 0, v[0:1]
	v_lshlrev_b32_e32 v189, 1, v52
	v_mov_b32_e32 v163, v162
	v_mov_b32_e32 v52, v58

; DI void attn_item(const bf16_t* P, bf16_t* Y, const float* sinkp, const float* rope, unsigned char* lds, bool is_ctx, int b, int blk, int hp) {
;     ...
;         if (sp + 1 < sp1) ATT_LOAD(sp + 1);
.LBB0_491:
	s_andn2_b64 vcc, exec, s[20:21]
	s_cbranch_vccnz .LBB0_493
	s_add_i32 s7, s24, s7
	s_lshl_b32 s7, s7, 7
	s_and_b64 s[20:21], s[44:45], exec
	s_cselect_b32 s7, 0, s7
	v_add_u32_e32 v2, s7, v146
	v_ashrrev_i32_e32 v2, 6, v2
	v_cndmask_b32_e64 v2, v170, v2, s[40:41]
	v_lshl_or_b32 v2, v2, 5, v171
	v_ashrrev_i32_e32 v3, 31, v2
	v_lshl_add_u64 v[14:15], v[2:3], 2, s[8:9]
	global_load_dwordx4 v[2:5], v[14:15], off
	global_load_dwordx4 v[6:9], v[14:15], off offset:16
	global_load_dwordx4 v[10:13], v[14:15], off offset:32
	s_nop 0
	global_load_dwordx4 v[14:17], v[14:15], off offset:48
	s_add_u32 s42, s18, s7
	s_addc_u32 s43, s19, 0
.LBB0_493:
	v_lshl_add_u64 v[18:19], s[42:43], 0, v[146:147]
	v_mad_u64_u32 v[30:31], s[20:21], v18, s28, v[152:153]
	v_mov_b32_e32 v18, v31
	v_mad_u64_u32 v[18:19], s[20:21], v19, s28, v[18:19]
	v_mov_b32_e32 v31, v18
	global_load_dwordx4 v[18:21], v[30:31], off offset:1024
	global_load_dwordx4 v[22:25], v[30:31], off offset:1088
	global_load_dwordx4 v[26:29], v[30:31], off offset:1280
	s_nop 0
	global_load_dwordx4 v[30:33], v[30:31], off offset:1344
